# conv/scan-operand phase: next-item operand prefetch moved behind the current item's dependent table loads
# speedup vs baseline: 1.0137x; 1.0039x over previous
; DI void unpack8(const u32x4 w, float (&f)[8]) { f[0] = bf_lo(w.x); f[1] = bf_hi(w.x); f[2] = bf_lo(w.y); f[3] = bf_hi(w.y); f[4] = bf_lo(w.z); f[5] = bf_hi(w.z); f[6] = bf_lo(w.w); f[7] = bf_hi(w.w); }
; DI void phase_prep(int l, int wv, bool last, bool dry = false) {
;     ...
;     auto item_load = [&](int item, PrepIn& P) {
;         const int chunk = item >> 4, h = (item >> 1) & 7, hc = (item & 1) * 64 + cg * 8, row = chunk * 64 + pp, c0 = h * DK + hc;
;         const bf16* prow = F.PROJ + (size_t)row * INW;
;         bool hasp, hasn;
;         if (row < NLAT) { hasp = pp != 0; hasn = pp != 63; } else { const int t = (row - NLAT) & (CTXL - 1); hasp = t != 0; hasn = t != CTXL - 1; }
;         const bf16* pprev = hasp ? prow - INW : prow; const bf16* pnext = hasn ? prow + INW : prow;
;         if (!(last && row >= NLAT)) {
;     ...
;         P.ccp = *(const u32x4*)(pprev + C_CC + c0); P.cvp = *(const u32x4*)(pprev + C_CV + c0); P.ccn = *(const u32x4*)(pnext + C_CC + c0); P.cvn = *(const u32x4*)(pnext + C_CV + c0);
;         P.q = *(const u32x4*)(prow + C_Q + c0); }
;         P.zf = *(const u32x4*)(prow + C_ZF + c0); P.zb = *(const u32x4*)(prow + C_ZB + c0); };
;     ...
;         const int chunk = item >> 4, h = (item >> 1) & 7, hc = (item & 1) * 64 + cg * 8, row = chunk * 64 + pp, c0 = h * DK + hc;
;         bf16* prow = F.PROJ + (size_t)row * INW;
;         bool hasp, hasn;
;         if (row < NLAT) { hasp = pp != 0; hasn = pp != 63; } else { const int t = (row - NLAT) & (CTXL - 1); hasp = t != 0; hasn = t != CTXL - 1; }
;         const bool full = !(last && row >= NLAT);
;         if (full) {   float cb[8], cc[8], cv[8], up[8], un[8], t0[8], t1[8], ya[8];
;     ...
;             if (hasp) { unpack8(P.ccp, t0); unpack8(P.cvp, t1);
; #pragma unroll
;                 for (int j = 0; j < 8; ++j) up[j] = t0[j] * t1[j]; }
.LBB0_361:
	s_add_i32 s65, s68, s34
	s_cmpk_lt_i32 s65, 0x1200
	s_cselect_b64 s[24:25], -1, 0
	s_cmpk_gt_i32 s65, 0x11ff
	s_cbranch_scc1 .LBB0_365
.LBB0_365:
	s_ashr_i32 s69, s68, 4
	v_lshl_add_u32 v120, s69, 6, v136
	v_readlane_b32 s0, v254, 33
	s_bfe_u32 s70, s68, 0x30001
	v_and_or_b32 v150, s64, 64, v137
	v_cmp_gt_i32_e32 vcc, s89, v120
	v_readlane_b32 s1, v254, 34
	v_lshl_or_b32 v128, s70, 7, v150
	v_ashrrev_i32_e32 v121, 31, v120
	s_or_b64 s[26:27], s[0:1], vcc
	s_and_saveexec_b64 s[28:29], s[26:27]
	s_cbranch_execz .LBB0_371
	s_waitcnt lgkmcnt(0)
	v_and_b32_e32 v80, 0xff, v120
	v_cmp_gt_i32_e32 vcc, s89, v120
	v_mov_b32_e32 v116, 0
	v_mov_b32_e32 v118, 0
	v_cndmask_b32_e32 v81, v80, v136, vcc
	v_cmp_ne_u32_e64 s[0:1], 0, v81
	v_mov_b32_e32 v119, 0
	v_mov_b32_e32 v122, 0
	v_mov_b32_e32 v123, 0
	v_mov_b32_e32 v126, 0
	v_mov_b32_e32 v127, 0
	v_mov_b32_e32 v112, 0
	v_mov_b32_e32 v113, 0
	s_and_saveexec_b64 s[30:31], s[0:1]
	s_cbranch_execz .LBB0_368
	s_waitcnt vmcnt(0)
	v_lshlrev_b32_e32 v83, 16, v8
	v_and_b32_e32 v82, 0xffff0000, v8
	v_lshlrev_b32_e32 v85, 16, v12
	v_and_b32_e32 v84, 0xffff0000, v12
	v_lshlrev_b32_e32 v87, 16, v9
	v_and_b32_e32 v86, 0xffff0000, v9
	v_lshlrev_b32_e32 v89, 16, v13
	v_and_b32_e32 v88, 0xffff0000, v13
	v_lshlrev_b32_e32 v90, 16, v10
	v_and_b32_e32 v91, 0xffff0000, v10
	v_lshlrev_b32_e32 v92, 16, v14
	v_and_b32_e32 v93, 0xffff0000, v14
	v_lshlrev_b32_e32 v94, 16, v11
	v_and_b32_e32 v95, 0xffff0000, v11
	v_lshlrev_b32_e32 v96, 16, v15
	v_and_b32_e32 v97, 0xffff0000, v15
	v_pk_mul_f32 v[118:119], v[82:83], v[84:85]
	v_pk_mul_f32 v[122:123], v[86:87], v[88:89]
	v_pk_mul_f32 v[126:127], v[90:91], v[92:93]
	v_pk_mul_f32 v[112:113], v[94:95], v[96:97]

; DI float frcp(float x) { return __builtin_amdgcn_rcpf(x); }
; DI void phase_prep(int l, int wv, bool last, bool dry = false) {
;     ...
;     auto item_load = [&](int item, PrepIn& P) {
;         const int chunk = item >> 4, h = (item >> 1) & 7, hc = (item & 1) * 64 + cg * 8, row = chunk * 64 + pp, c0 = h * DK + hc;
;         const bf16* prow = F.PROJ + (size_t)row * INW;
;         bool hasp, hasn;
;         if (row < NLAT) { hasp = pp != 0; hasn = pp != 63; } else { const int t = (row - NLAT) & (CTXL - 1); hasp = t != 0; hasn = t != CTXL - 1; }
;         const bf16* pprev = hasp ? prow - INW : prow; const bf16* pnext = hasn ? prow + INW : prow;
;         if (!(last && row >= NLAT)) {
;     ...
;         P.ccp = *(const u32x4*)(pprev + C_CC + c0); P.cvp = *(const u32x4*)(pprev + C_CV + c0); P.ccn = *(const u32x4*)(pnext + C_CC + c0); P.cvn = *(const u32x4*)(pnext + C_CV + c0);
;         P.q = *(const u32x4*)(prow + C_Q + c0); }
;         P.zf = *(const u32x4*)(prow + C_ZF + c0); P.zb = *(const u32x4*)(prow + C_ZB + c0); };
;     ...
;             const f32x4 lfa = *(const f32x4*)(lbt + c0), lfc = *(const f32x4*)(lbt + c0 + 4), lba = *(const f32x4*)(lbt + DC + c0), lbc = *(const f32x4*)(lbt + DC + c0 + 4);
; #pragma unroll
;             for (int i = 0; i < 8; ++i) { const float lbf = i < 4 ? lfa[i & 3] : lfc[i & 3], lbb = i < 4 ? lba[i & 3] : lbc[i & 3];
;                 const float ef = __expf(fminf(fmaxf(-zf[i], -80.f), 80.f)), eb = __expf(fminf(fmaxf(-zb[i], -80.f), 80.f)), sf = frcp(1.0f + ef), sb = frcp(1.0f + eb);
;                 lff[i] = __logf(fmaxf(lbf + (1.0f - lbf) * sf, F_MIN)); kf[i] = (1.0f - lbf) * (ef * sf);
;                 lfb[i] = __logf(fmaxf(lbb + (1.0f - lbb) * sb, F_MIN)); kb[i] = (1.0f - lbb) * (eb * sb);
;                 qs[i] = q[i] * frcp(1.0f + __expf(-q[i])) * QSCALE; }
.LBB0_373:
	s_or_b64 exec, exec, s[0:1]
	v_lshlrev_b32_e32 v88, 2, v128
	global_load_dwordx4 v[84:87], v88, s[12:13] offset:16
	global_load_dwordx4 v[92:95], v88, s[12:13]
	s_waitcnt lgkmcnt(0)
	global_load_dwordx4 v[80:83], v88, s[22:23] offset:16
	s_nop 0
	global_load_dwordx4 v[88:91], v88, s[22:23]
	s_waitcnt vmcnt(0)
	s_cmpk_gt_i32 s65, 0x11ff
	s_cbranch_scc1 .Lprep_pf_skip_A
	v_mov_b32_e32 v209, 0
	s_add_i32 s97, s62, s63
	s_add_i32 s96, s61, s64
	s_andn2_b32 s97, s97, 63
	v_add_u32_e32 v75, s97, v136
	s_and_b32 s96, s96, 0x3c0
	v_mov_b64_e32 v[72:73], s[8:9]
	v_or_b32_e32 v74, s96, v137
	v_mad_i64_i32 v[72:73], s[96:97], v75, s66, v[72:73]
	v_readlane_b32 s96, v254, 33
	v_cmp_gt_i32_e32 vcc, s89, v75
	v_readlane_b32 s97, v254, 34
	s_or_b64 s[96:97], s[96:97], vcc
	s_and_saveexec_b64 s[94:95], s[96:97]
	s_xor_b64 s[94:95], exec, s[94:95]
	s_cbranch_execz .LBB0_364
	v_and_b32_e32 v32, 0xff, v75
	s_movk_i32 s96, 0xff
	v_cmp_gt_i32_e32 vcc, s89, v75
	v_cmp_ne_u32_e64 s[96:97], s96, v32
	v_cndmask_b32_e64 v34, 0, 1, s[36:37]
	v_cndmask_b32_e32 v33, v32, v136, vcc
	v_cndmask_b32_e64 v32, 0, 1, s[96:97]
	v_cndmask_b32_e32 v32, v32, v34, vcc
	v_and_b32_e32 v32, 1, v32
	v_cmp_eq_u32_e32 vcc, 1, v32
	s_nop 1
	v_cndmask_b32_e32 v208, 0, v241, vcc
	v_lshl_add_u64 v[56:57], v[72:73], 0, v[208:209]
	v_cmp_eq_u32_e32 vcc, 0, v33
	v_lshlrev_b32_e32 v208, 1, v74
	v_lshl_add_u64 v[42:43], v[72:73], 0, v[208:209]
	v_cndmask_b32_e64 v33, -1, 0, vcc
	v_cndmask_b32_e64 v32, v251, 0, vcc
	v_lshl_add_u64 v[40:41], v[72:73], 0, v[32:33]
	v_add_co_u32_e32 v68, vcc, s67, v42
	v_lshl_add_u64 v[40:41], v[40:41], 0, v[208:209]
	s_nop 0
	v_addc_co_u32_e32 v69, vcc, 0, v43, vcc
	v_add_co_u32_e32 v48, vcc, 0x1000, v40
	v_lshl_add_u64 v[56:57], v[56:57], 0, v[208:209]
	s_nop 0
	v_addc_co_u32_e32 v49, vcc, 0, v41, vcc
	v_add_co_u32_e32 v60, vcc, 0x1000, v56
	global_load_dwordx4 v[32:35], v[42:43], off
	global_load_dwordx4 v[36:39], v[42:43], off offset:2048
	v_addc_co_u32_e32 v61, vcc, 0, v57, vcc
	global_load_dwordx4 v[40:43], v[40:41], off offset:2048
	s_nop 0
	global_load_dwordx4 v[48:51], v[48:49], off
	s_nop 0
	global_load_dwordx4 v[56:59], v[56:57], off offset:2048
	s_nop 0
	global_load_dwordx4 v[64:67], v[60:61], off
	s_nop 0
	global_load_dwordx4 v[60:63], v[68:69], off
	s_nop 0
	global_load_dwordx4 v[68:71], v[68:69], off offset:2048
.LBB0_364:
	s_andn2_saveexec_b64 s[96:97], s[94:95]
	s_or_b64 exec, exec, s[96:97]
	v_lshlrev_b32_e32 v208, 1, v74
	v_lshl_add_u64 v[72:73], v[72:73], 0, v[208:209]
	v_add_co_u32_e32 v76, vcc, 0x2000, v72
	s_nop 1
	v_addc_co_u32_e32 v77, vcc, 0, v73, vcc
	global_load_dwordx4 v[72:75], v[76:77], off
	s_nop 0
	global_load_dwordx4 v[76:79], v[76:77], off offset:2048
.Lprep_pf_skip_A:
	v_lshlrev_b32_e32 v98, 16, v44
	v_max_f32_e64 v98, -v98, -v98
	s_mov_b32 s29, 0xc2a00000
	v_med3_f32 v98, v98, s29, v245
	v_mul_f32_e32 v98, 0x3fb8aa3b, v98
	v_lshlrev_b32_e32 v111, 16, v52
	v_exp_f32_e32 v110, v98
	v_max_f32_e64 v98, -v111, -v111
	v_med3_f32 v98, v98, s29, v245
	v_mul_f32_e32 v98, 0x3fb8aa3b, v98
	v_exp_f32_e32 v111, v98
	v_add_f32_e32 v98, 1.0, v110
	v_rcp_f32_e32 v131, v98
	s_mov_b32 s28, 0x800000
	v_add_f32_e32 v98, 1.0, v111
	v_rcp_f32_e32 v132, v98
	s_mov_b32 s30, 0x3f317217
	s_mov_b32 s31, 0x7f800000
	v_and_b32_e32 v107, 0xffff0000, v44
	v_and_b32_e32 v112, 0xffff0000, v52
	v_lshlrev_b32_e32 v108, 16, v45
	v_lshlrev_b32_e32 v109, 16, v53
	v_and_b32_e32 v105, 0xffff0000, v45
	v_and_b32_e32 v106, 0xffff0000, v53
	v_lshlrev_b32_e32 v103, 16, v46
	v_lshlrev_b32_e32 v104, 16, v54
	v_and_b32_e32 v101, 0xffff0000, v46
	v_and_b32_e32 v102, 0xffff0000, v54
	v_lshlrev_b32_e32 v99, 16, v47
	v_lshlrev_b32_e32 v100, 16, v55
	v_and_b32_e32 v96, 0xffff0000, v47
	v_and_b32_e32 v97, 0xffff0000, v55
	v_add_u32_e32 v149, s35, v144
	s_barrier
	v_sub_f32_e32 v172, 1.0, v84
	v_sub_f32_e32 v133, 1.0, v92
	v_fma_f32 v92, v131, v133, v92
	v_max_f32_e32 v92, 0xda24260, v92
	v_cmp_gt_f32_e32 vcc, s28, v92
	v_sub_f32_e32 v134, 1.0, v88
	v_fma_f32 v88, v132, v134, v88
	v_cndmask_b32_e64 v98, 0, 32, vcc
	v_ldexp_f32 v92, v92, v98
	v_log_f32_e32 v92, v92
	v_max_f32_e32 v88, 0xda24260, v88
	v_sub_f32_e32 v154, 1.0, v93
	v_sub_f32_e32 v155, 1.0, v89
	v_mul_f32_e32 v98, 0x3f317217, v92
	v_fma_f32 v98, v92, s30, -v98
	v_fmac_f32_e32 v98, 0x3377d1cf, v92
	v_fmac_f32_e32 v98, 0x3f317217, v92
	v_cmp_lt_f32_e64 s[0:1], |v92|, s31
	v_sub_f32_e32 v160, 1.0, v94
	v_sub_f32_e32 v161, 1.0, v90
	v_cndmask_b32_e64 v92, v92, v98, s[0:1]
	v_cndmask_b32_e32 v98, 0, v246, vcc
	v_cmp_gt_f32_e32 vcc, s28, v88
	v_sub_f32_e32 v92, v92, v98
	v_sub_f32_e32 v166, 1.0, v95
	v_cndmask_b32_e64 v98, 0, 32, vcc
	v_ldexp_f32 v88, v88, v98
	v_log_f32_e32 v88, v88
	v_sub_f32_e32 v167, 1.0, v91
	v_sub_f32_e32 v173, 1.0, v80
	v_sub_f32_e32 v178, 1.0, v85
	v_mul_f32_e32 v98, 0x3f317217, v88
	v_fma_f32 v98, v88, s30, -v98
	v_fmac_f32_e32 v98, 0x3377d1cf, v88
	v_fmac_f32_e32 v98, 0x3f317217, v88
	v_cmp_lt_f32_e64 s[0:1], |v88|, s31
	v_sub_f32_e32 v179, 1.0, v81
	v_sub_f32_e32 v184, 1.0, v86
	v_cndmask_b32_e64 v88, v88, v98, s[0:1]
	v_cndmask_b32_e32 v98, 0, v246, vcc
	v_sub_f32_e32 v98, v88, v98
	v_max_f32_e64 v88, -v107, -v107
	v_med3_f32 v88, v88, s29, v245
	v_mul_f32_e32 v88, 0x3fb8aa3b, v88
	v_exp_f32_e32 v135, v88
	v_max_f32_e64 v88, -v112, -v112
	v_med3_f32 v88, v88, s29, v245
	v_mul_f32_e32 v88, 0x3fb8aa3b, v88
	v_exp_f32_e32 v151, v88
	v_add_f32_e32 v88, 1.0, v135
	v_rcp_f32_e32 v152, v88
	v_sub_f32_e32 v185, 1.0, v82
	v_add_f32_e32 v88, 1.0, v151
	v_rcp_f32_e32 v153, v88
	v_fma_f32 v88, v152, v154, v93
	v_max_f32_e32 v88, 0xda24260, v88
	v_cmp_gt_f32_e32 vcc, s28, v88
	v_sub_f32_e32 v190, 1.0, v87
; DI float frcp(float x) { return __builtin_amdgcn_rcpf(x); }
; DI void phase_prep(int l, int wv, bool last, bool dry = false) {
;     ...
;             const f32x4 lfa = *(const f32x4*)(lbt + c0), lfc = *(const f32x4*)(lbt + c0 + 4), lba = *(const f32x4*)(lbt + DC + c0), lbc = *(const f32x4*)(lbt + DC + c0 + 4);
; #pragma unroll
;             for (int i = 0; i < 8; ++i) { const float lbf = i < 4 ? lfa[i & 3] : lfc[i & 3], lbb = i < 4 ? lba[i & 3] : lbc[i & 3];
;                 const float ef = __expf(fminf(fmaxf(-zf[i], -80.f), 80.f)), eb = __expf(fminf(fmaxf(-zb[i], -80.f), 80.f)), sf = frcp(1.0f + ef), sb = frcp(1.0f + eb);
;                 lff[i] = __logf(fmaxf(lbf + (1.0f - lbf) * sf, F_MIN)); kf[i] = (1.0f - lbf) * (ef * sf);
;                 lfb[i] = __logf(fmaxf(lbb + (1.0f - lbb) * sb, F_MIN)); kb[i] = (1.0f - lbb) * (eb * sb);
;                 qs[i] = q[i] * frcp(1.0f + __expf(-q[i])) * QSCALE; }
;         }
; #pragma unroll
;         for (int d = 1; d < 8; d <<= 1) {
; #pragma unroll
;             for (int i = 0; i < 8; ++i) { const float o = __shfl_up(lff[i], 8 * d); if (pl >= d) lff[i] += o; const float o2 = __shfl_down(lfb[i], 8 * d); if (pl + d < 8) lfb[i] += o2; } }
	v_sub_f32_e32 v191, 1.0, v83
	v_cndmask_b32_e64 v93, 0, 32, vcc
	v_ldexp_f32 v88, v88, v93
	v_log_f32_e32 v88, v88
	s_nop 0
	v_mul_f32_e32 v93, 0x3f317217, v88
	v_fma_f32 v93, v88, s30, -v93
	v_fmac_f32_e32 v93, 0x3377d1cf, v88
	v_fmac_f32_e32 v93, 0x3f317217, v88
	v_cmp_lt_f32_e64 s[0:1], |v88|, s31
	s_nop 1
	v_cndmask_b32_e64 v88, v88, v93, s[0:1]
	v_cndmask_b32_e32 v93, 0, v246, vcc
	v_sub_f32_e32 v93, v88, v93
	v_fma_f32 v88, v153, v155, v89
	v_max_f32_e32 v88, 0xda24260, v88
	v_cmp_gt_f32_e32 vcc, s28, v88
	s_nop 1
	v_cndmask_b32_e64 v89, 0, 32, vcc
	v_ldexp_f32 v88, v88, v89
	v_log_f32_e32 v88, v88
	s_nop 0
	v_mul_f32_e32 v89, 0x3f317217, v88
	v_fma_f32 v89, v88, s30, -v89
	v_fmac_f32_e32 v89, 0x3377d1cf, v88
	v_fmac_f32_e32 v89, 0x3f317217, v88
	v_cmp_lt_f32_e64 s[0:1], |v88|, s31
	s_nop 1
	v_cndmask_b32_e64 v88, v88, v89, s[0:1]
	v_cndmask_b32_e32 v89, 0, v246, vcc
	v_sub_f32_e32 v107, v88, v89
	v_max_f32_e64 v88, -v108, -v108
	v_med3_f32 v88, v88, s29, v245
	v_mul_f32_e32 v88, 0x3fb8aa3b, v88
	v_exp_f32_e32 v156, v88
	v_max_f32_e64 v88, -v109, -v109
	v_med3_f32 v88, v88, s29, v245
	v_mul_f32_e32 v88, 0x3fb8aa3b, v88
	v_exp_f32_e32 v157, v88
	v_add_f32_e32 v88, 1.0, v156
	v_rcp_f32_e32 v158, v88
	v_add_f32_e32 v88, 1.0, v157
	v_rcp_f32_e32 v159, v88
	v_fma_f32 v88, v158, v160, v94
	v_max_f32_e32 v88, 0xda24260, v88
	v_cmp_gt_f32_e32 vcc, s28, v88
	s_nop 1
	v_cndmask_b32_e64 v89, 0, 32, vcc
	v_ldexp_f32 v88, v88, v89
	v_log_f32_e32 v88, v88
	s_nop 0
	v_mul_f32_e32 v89, 0x3f317217, v88
	v_fma_f32 v89, v88, s30, -v89
	v_fmac_f32_e32 v89, 0x3377d1cf, v88
	v_fmac_f32_e32 v89, 0x3f317217, v88
	v_cmp_lt_f32_e64 s[0:1], |v88|, s31
	s_nop 1
	v_cndmask_b32_e64 v88, v88, v89, s[0:1]
	v_cndmask_b32_e32 v89, 0, v246, vcc
	v_sub_f32_e32 v88, v88, v89
	v_fma_f32 v89, v159, v161, v90
	v_max_f32_e32 v89, 0xda24260, v89
	v_cmp_gt_f32_e32 vcc, s28, v89
	s_nop 1
	v_cndmask_b32_e64 v90, 0, 32, vcc
	v_ldexp_f32 v89, v89, v90
	v_log_f32_e32 v89, v89
	s_nop 0
	v_mul_f32_e32 v90, 0x3f317217, v89
	v_fma_f32 v90, v89, s30, -v90
	v_fmac_f32_e32 v90, 0x3377d1cf, v89
	v_fmac_f32_e32 v90, 0x3f317217, v89
	v_cmp_lt_f32_e64 s[0:1], |v89|, s31
	s_nop 1
	v_cndmask_b32_e64 v89, v89, v90, s[0:1]
	v_cndmask_b32_e32 v90, 0, v246, vcc
	v_sub_f32_e32 v90, v89, v90
	v_max_f32_e64 v89, -v105, -v105
	v_med3_f32 v89, v89, s29, v245
	v_mul_f32_e32 v89, 0x3fb8aa3b, v89
	v_exp_f32_e32 v162, v89
	v_max_f32_e64 v89, -v106, -v106
	v_med3_f32 v89, v89, s29, v245
	v_mul_f32_e32 v89, 0x3fb8aa3b, v89
	v_exp_f32_e32 v163, v89
	v_add_f32_e32 v89, 1.0, v162
	v_rcp_f32_e32 v164, v89
	ds_bpermute_b32 v105, v138, v93
	v_add_f32_e32 v89, 1.0, v163
	v_rcp_f32_e32 v165, v89
	v_fmac_f32_e32 v95, v164, v166
	v_max_f32_e32 v89, 0xda24260, v95
	v_cmp_gt_f32_e32 vcc, s28, v89
	v_fmac_f32_e32 v91, v165, v167
	v_max_f32_e32 v91, 0xda24260, v91
	v_cndmask_b32_e64 v94, 0, 32, vcc
	v_ldexp_f32 v89, v89, v94
	v_log_f32_e32 v89, v89
	ds_bpermute_b32 v95, v139, v98
	v_mul_f32_e32 v94, 0x3f317217, v89
	v_fma_f32 v94, v89, s30, -v94
	v_fmac_f32_e32 v94, 0x3377d1cf, v89
	v_fmac_f32_e32 v94, 0x3f317217, v89
	v_cmp_lt_f32_e64 s[0:1], |v89|, s31
	s_waitcnt lgkmcnt(0)
	v_cndmask_b32_e64 v95, v247, v95, s[40:41]
	v_add_f32_e32 v95, v95, v98
	v_cndmask_b32_e64 v89, v89, v94, s[0:1]
	v_cndmask_b32_e32 v94, 0, v246, vcc
	v_cmp_gt_f32_e32 vcc, s28, v91
	v_sub_f32_e32 v89, v89, v94
	ds_bpermute_b32 v108, v138, v89
	v_cndmask_b32_e64 v94, 0, 32, vcc
	v_ldexp_f32 v91, v91, v94
	v_log_f32_e32 v91, v91
	s_nop 0
	v_mul_f32_e32 v94, 0x3f317217, v91
	v_fma_f32 v94, v91, s30, -v94
	v_fmac_f32_e32 v94, 0x3377d1cf, v91
	v_fmac_f32_e32 v94, 0x3f317217, v91
	v_cmp_lt_f32_e64 s[0:1], |v91|, s31
	s_nop 1
	v_cndmask_b32_e64 v91, v91, v94, s[0:1]
	v_cndmask_b32_e32 v94, 0, v246, vcc
	v_sub_f32_e32 v91, v91, v94
	v_max_f32_e64 v94, -v103, -v103
	v_med3_f32 v94, v94, s29, v245
	v_mul_f32_e32 v94, 0x3fb8aa3b, v94
	v_exp_f32_e32 v168, v94
	v_max_f32_e64 v94, -v104, -v104
	v_med3_f32 v94, v94, s29, v245
	v_mul_f32_e32 v94, 0x3fb8aa3b, v94
	v_exp_f32_e32 v169, v94
	v_add_f32_e32 v94, 1.0, v168
	v_rcp_f32_e32 v170, v94
	v_add_f32_e32 v94, 1.0, v169
	v_rcp_f32_e32 v171, v94
	v_fma_f32 v84, v170, v172, v84
	v_max_f32_e32 v84, 0xda24260, v84
	v_cmp_gt_f32_e32 vcc, s28, v84
	v_fma_f32 v80, v171, v173, v80
	v_max_f32_e32 v80, 0xda24260, v80
	v_cndmask_b32_e64 v94, 0, 32, vcc
	v_ldexp_f32 v84, v84, v94
	v_log_f32_e32 v84, v84
	s_nop 0
	v_mul_f32_e32 v94, 0x3f317217, v84
	v_fma_f32 v94, v84, s30, -v94
	v_fmac_f32_e32 v94, 0x3377d1cf, v84
	v_fmac_f32_e32 v94, 0x3f317217, v84
	v_cmp_lt_f32_e64 s[0:1], |v84|, s31
	s_nop 1
	v_cndmask_b32_e64 v84, v84, v94, s[0:1]
	v_cndmask_b32_e32 v94, 0, v246, vcc
	v_cmp_gt_f32_e32 vcc, s28, v80
	v_sub_f32_e32 v84, v84, v94
	ds_bpermute_b32 v109, v138, v84
	v_cndmask_b32_e64 v94, 0, 32, vcc
	v_ldexp_f32 v80, v80, v94
	v_log_f32_e32 v80, v80
	s_nop 0
	v_mul_f32_e32 v94, 0x3f317217, v80
	v_fma_f32 v94, v80, s30, -v94
	v_fmac_f32_e32 v94, 0x3377d1cf, v80
	v_fmac_f32_e32 v94, 0x3f317217, v80
	v_cmp_lt_f32_e64 s[0:1], |v80|, s31
	s_nop 1
	v_cndmask_b32_e64 v80, v80, v94, s[0:1]
	v_cndmask_b32_e32 v94, 0, v246, vcc
	v_sub_f32_e32 v80, v80, v94
	v_max_f32_e64 v94, -v101, -v101
	v_med3_f32 v94, v94, s29, v245
	v_mul_f32_e32 v94, 0x3fb8aa3b, v94
	v_exp_f32_e32 v174, v94
	v_max_f32_e64 v94, -v102, -v102
	v_med3_f32 v94, v94, s29, v245
	v_mul_f32_e32 v94, 0x3fb8aa3b, v94
	v_exp_f32_e32 v175, v94
	v_add_f32_e32 v94, 1.0, v174
	v_rcp_f32_e32 v176, v94
	v_add_f32_e32 v94, 1.0, v175
	v_rcp_f32_e32 v177, v94
	v_fma_f32 v85, v176, v178, v85
	v_max_f32_e32 v85, 0xda24260, v85
	v_cmp_gt_f32_e32 vcc, s28, v85
	v_fma_f32 v81, v177, v179, v81
; DI float frcp(float x) { return __builtin_amdgcn_rcpf(x); }
; DI void phase_prep(int l, int wv, bool last, bool dry = false) {
;     ...
;             const f32x4 lfa = *(const f32x4*)(lbt + c0), lfc = *(const f32x4*)(lbt + c0 + 4), lba = *(const f32x4*)(lbt + DC + c0), lbc = *(const f32x4*)(lbt + DC + c0 + 4);
; #pragma unroll
;             for (int i = 0; i < 8; ++i) { const float lbf = i < 4 ? lfa[i & 3] : lfc[i & 3], lbb = i < 4 ? lba[i & 3] : lbc[i & 3];
;                 const float ef = __expf(fminf(fmaxf(-zf[i], -80.f), 80.f)), eb = __expf(fminf(fmaxf(-zb[i], -80.f), 80.f)), sf = frcp(1.0f + ef), sb = frcp(1.0f + eb);
;                 lff[i] = __logf(fmaxf(lbf + (1.0f - lbf) * sf, F_MIN)); kf[i] = (1.0f - lbf) * (ef * sf);
;                 lfb[i] = __logf(fmaxf(lbb + (1.0f - lbb) * sb, F_MIN)); kb[i] = (1.0f - lbb) * (eb * sb);
;                 qs[i] = q[i] * frcp(1.0f + __expf(-q[i])) * QSCALE; }
;         }
; #pragma unroll
;         for (int d = 1; d < 8; d <<= 1) {
; #pragma unroll
;             for (int i = 0; i < 8; ++i) { const float o = __shfl_up(lff[i], 8 * d); if (pl >= d) lff[i] += o; const float o2 = __shfl_down(lfb[i], 8 * d); if (pl + d < 8) lfb[i] += o2; } }
	v_max_f32_e32 v81, 0xda24260, v81
	v_cndmask_b32_e64 v94, 0, 32, vcc
	v_ldexp_f32 v85, v85, v94
	v_log_f32_e32 v85, v85
	s_nop 0
	v_mul_f32_e32 v94, 0x3f317217, v85
	v_fma_f32 v94, v85, s30, -v94
	v_fmac_f32_e32 v94, 0x3377d1cf, v85
	v_fmac_f32_e32 v94, 0x3f317217, v85
	v_cmp_lt_f32_e64 s[0:1], |v85|, s31
	s_nop 1
	v_cndmask_b32_e64 v85, v85, v94, s[0:1]
	v_cndmask_b32_e32 v94, 0, v246, vcc
	v_cmp_gt_f32_e32 vcc, s28, v81
	v_sub_f32_e32 v85, v85, v94
	ds_bpermute_b32 v112, v138, v85
	v_cndmask_b32_e64 v94, 0, 32, vcc
	v_ldexp_f32 v81, v81, v94
	v_log_f32_e32 v81, v81
	s_nop 0
	v_mul_f32_e32 v94, 0x3f317217, v81
	v_fma_f32 v94, v81, s30, -v94
	v_fmac_f32_e32 v94, 0x3377d1cf, v81
	v_fmac_f32_e32 v94, 0x3f317217, v81
	v_cmp_lt_f32_e64 s[0:1], |v81|, s31
	s_nop 1
	v_cndmask_b32_e64 v81, v81, v94, s[0:1]
	v_cndmask_b32_e32 v94, 0, v246, vcc
	v_sub_f32_e32 v81, v81, v94
	v_max_f32_e64 v94, -v99, -v99
	v_med3_f32 v94, v94, s29, v245
	v_mul_f32_e32 v94, 0x3fb8aa3b, v94
	v_exp_f32_e32 v180, v94
	v_max_f32_e64 v94, -v100, -v100
	v_med3_f32 v94, v94, s29, v245
	v_mul_f32_e32 v94, 0x3fb8aa3b, v94
	v_exp_f32_e32 v181, v94
	v_add_f32_e32 v94, 1.0, v180
	v_rcp_f32_e32 v182, v94
	v_add_f32_e32 v94, 1.0, v181
	v_rcp_f32_e32 v183, v94
	v_fma_f32 v86, v182, v184, v86
	v_max_f32_e32 v86, 0xda24260, v86
	v_cmp_gt_f32_e32 vcc, s28, v86
	v_fma_f32 v82, v183, v185, v82
	v_max_f32_e32 v82, 0xda24260, v82
	v_cndmask_b32_e64 v94, 0, 32, vcc
	v_ldexp_f32 v86, v86, v94
	v_log_f32_e32 v86, v86
	s_nop 0
	v_mul_f32_e32 v94, 0x3f317217, v86
	v_fma_f32 v94, v86, s30, -v94
	v_fmac_f32_e32 v94, 0x3377d1cf, v86
	v_fmac_f32_e32 v94, 0x3f317217, v86
	v_cmp_lt_f32_e64 s[0:1], |v86|, s31
	s_nop 1
	v_cndmask_b32_e64 v86, v86, v94, s[0:1]
	v_cndmask_b32_e32 v94, 0, v246, vcc
	v_cmp_gt_f32_e32 vcc, s28, v82
	v_sub_f32_e32 v86, v86, v94
	ds_bpermute_b32 v114, v138, v86
	v_cndmask_b32_e64 v94, 0, 32, vcc
	v_ldexp_f32 v82, v82, v94
	v_log_f32_e32 v82, v82
	s_nop 0
	v_mul_f32_e32 v94, 0x3f317217, v82
	v_fma_f32 v94, v82, s30, -v94
	v_fmac_f32_e32 v94, 0x3377d1cf, v82
	v_fmac_f32_e32 v94, 0x3f317217, v82
	v_cmp_lt_f32_e64 s[0:1], |v82|, s31
	s_nop 1
	v_cndmask_b32_e64 v82, v82, v94, s[0:1]
	v_cndmask_b32_e32 v94, 0, v246, vcc
	v_sub_f32_e32 v82, v82, v94
	v_max_f32_e64 v94, -v96, -v96
	v_med3_f32 v94, v94, s29, v245
	v_mul_f32_e32 v94, 0x3fb8aa3b, v94
	ds_bpermute_b32 v96, v139, v107
	v_exp_f32_e32 v186, v94
	v_max_f32_e64 v94, -v97, -v97
	v_med3_f32 v94, v94, s29, v245
	v_mul_f32_e32 v94, 0x3fb8aa3b, v94
	v_exp_f32_e32 v187, v94
	v_add_f32_e32 v94, 1.0, v186
	s_waitcnt lgkmcnt(0)
	v_cndmask_b32_e64 v96, v247, v96, s[40:41]
	v_rcp_f32_e32 v188, v94
	v_add_f32_e32 v97, v107, v96
	ds_bpermute_b32 v96, v139, v90
	v_add_f32_e32 v94, 1.0, v187
	v_fmac_f32_e32 v87, v188, v190
	v_max_f32_e32 v87, 0xda24260, v87
	v_cmp_gt_f32_e32 vcc, s28, v87
	s_waitcnt lgkmcnt(0)
	v_cndmask_b32_e64 v96, v247, v96, s[40:41]
	v_add_f32_e32 v90, v90, v96
	ds_bpermute_b32 v96, v139, v91
	v_rcp_f32_e32 v189, v94
	v_cndmask_b32_e64 v94, 0, 32, vcc
	v_ldexp_f32 v87, v87, v94
	v_log_f32_e32 v87, v87
	s_waitcnt lgkmcnt(0)
	v_cndmask_b32_e64 v96, v247, v96, s[40:41]
	v_add_f32_e32 v91, v91, v96
	ds_bpermute_b32 v96, v139, v80
	v_mul_f32_e32 v94, 0x3f317217, v87
	v_fma_f32 v94, v87, s30, -v94
	v_fmac_f32_e32 v94, 0x3377d1cf, v87
	v_fmac_f32_e32 v83, v189, v191
	v_fmac_f32_e32 v94, 0x3f317217, v87
	v_cmp_lt_f32_e64 s[0:1], |v87|, s31
	v_max_f32_e32 v83, 0xda24260, v83
	s_waitcnt lgkmcnt(0)
	v_cndmask_b32_e64 v96, v247, v96, s[40:41]
	v_cndmask_b32_e64 v87, v87, v94, s[0:1]
	v_cndmask_b32_e32 v94, 0, v246, vcc
	v_cmp_gt_f32_e32 vcc, s28, v83
	v_sub_f32_e32 v87, v87, v94
	v_add_f32_e32 v80, v80, v96
	v_cndmask_b32_e64 v94, 0, 32, vcc
	ds_bpermute_b32 v96, v139, v81
	v_ldexp_f32 v83, v83, v94
	v_log_f32_e32 v83, v83
	ds_bpermute_b32 v107, v138, v88
	ds_bpermute_b32 v115, v138, v87
	s_waitcnt lgkmcnt(2)
; #define LAS __attribute__((address_space(3)))
; DI void phase_prep(int l, int wv, bool last, bool dry = false) {
;     ...
;         for (int d = 1; d < 8; d <<= 1) {
; #pragma unroll
;             for (int i = 0; i < 8; ++i) { const float o = __shfl_up(lff[i], 8 * d); if (pl >= d) lff[i] += o; const float o2 = __shfl_down(lfb[i], 8 * d); if (pl + d < 8) lfb[i] += o2; } }
;         __syncthreads();
;         if (pl == 7) { *(LAS f32x4*)(L + O_TOTF + (w * 64 + cg * 8) * 4) = (f32x4){lff[0], lff[1], lff[2], lff[3]}; *(LAS f32x4*)(L + O_TOTF + (w * 64 + cg * 8 + 4) * 4) = (f32x4){lff[4], lff[5], lff[6], lff[7]}; }
;         if (pl == 0) { *(LAS f32x4*)(L + O_TOTB + (w * 64 + cg * 8) * 4) = (f32x4){lfb[0], lfb[1], lfb[2], lfb[3]}; *(LAS f32x4*)(L + O_TOTB + (w * 64 + cg * 8 + 4) * 4) = (f32x4){lfb[4], lfb[5], lfb[6], lfb[7]}; }
	v_cndmask_b32_e64 v96, v247, v96, s[40:41]
	v_mul_f32_e32 v94, 0x3f317217, v83
	v_add_f32_e32 v81, v81, v96
	ds_bpermute_b32 v96, v139, v82
	v_fma_f32 v94, v83, s30, -v94
	v_fmac_f32_e32 v94, 0x3377d1cf, v83
	v_fmac_f32_e32 v94, 0x3f317217, v83
	v_cmp_lt_f32_e64 s[0:1], |v83|, s31
	s_waitcnt lgkmcnt(0)
	v_cndmask_b32_e64 v96, v247, v96, s[40:41]
	v_add_f32_e32 v82, v82, v96
	v_cndmask_b32_e64 v83, v83, v94, s[0:1]
	v_cndmask_b32_e32 v94, 0, v246, vcc
	v_sub_f32_e32 v83, v83, v94
	ds_bpermute_b32 v96, v139, v83
	ds_bpermute_b32 v94, v138, v92
	s_waitcnt lgkmcnt(1)
	v_cndmask_b32_e64 v96, v247, v96, s[40:41]
	v_add_f32_e32 v83, v83, v96
	ds_bpermute_b32 v96, v141, v95
	s_waitcnt lgkmcnt(0)
	v_add_f32_e32 v96, v95, v96
	v_cndmask_b32_e64 v96, v95, v96, s[44:45]
	ds_bpermute_b32 v95, v141, v97
	ds_bpermute_b32 v104, v143, v96
	s_waitcnt lgkmcnt(1)
	v_add_f32_e32 v95, v97, v95
	v_cndmask_b32_e64 v97, v97, v95, s[44:45]
	ds_bpermute_b32 v95, v141, v90
	ds_bpermute_b32 v106, v143, v97
	s_waitcnt lgkmcnt(1)
	v_add_f32_e32 v95, v90, v95
	v_cndmask_b32_e64 v98, v90, v95, s[44:45]
	ds_bpermute_b32 v90, v141, v91
	v_cndmask_b32_e64 v95, v115, v247, s[38:39]
	s_waitcnt lgkmcnt(0)
	v_add_f32_e32 v90, v91, v90
	v_cndmask_b32_e64 v99, v91, v90, s[44:45]
	ds_bpermute_b32 v90, v141, v80
	s_waitcnt lgkmcnt(0)
	v_add_f32_e32 v90, v80, v90
	v_cndmask_b32_e64 v100, v80, v90, s[44:45]
	ds_bpermute_b32 v80, v141, v81
	s_waitcnt lgkmcnt(0)
	v_add_f32_e32 v80, v81, v80
	v_cndmask_b32_e64 v101, v81, v80, s[44:45]
	ds_bpermute_b32 v80, v141, v82
	v_cndmask_b32_e64 v81, v105, v247, s[38:39]
	ds_bpermute_b32 v105, v143, v98
	ds_bpermute_b32 v113, v143, v101
	s_waitcnt lgkmcnt(2)
	v_add_f32_e32 v80, v82, v80
	v_cndmask_b32_e64 v102, v82, v80, s[44:45]
	ds_bpermute_b32 v80, v141, v83
	s_waitcnt lgkmcnt(0)
	v_add_f32_e32 v80, v83, v80
	v_cndmask_b32_e64 v103, v83, v80, s[44:45]
	v_cndmask_b32_e64 v80, v94, v247, s[38:39]
	v_pk_add_f32 v[80:81], v[92:93], v[80:81]
	ds_bpermute_b32 v82, v140, v80
	ds_bpermute_b32 v83, v140, v81
	v_cndmask_b32_e64 v93, v112, v247, s[38:39]
	v_cndmask_b32_e64 v92, v109, v247, s[38:39]
	v_cndmask_b32_e64 v94, v114, v247, s[38:39]
	v_pk_add_f32 v[84:85], v[84:85], v[92:93]
	s_waitcnt lgkmcnt(0)
	v_pk_add_f32 v[82:83], v[80:81], v[82:83]
	v_pk_add_f32 v[86:87], v[86:87], v[94:95]
	v_cndmask_b32_e64 v91, v83, v81, s[42:43]
	v_cndmask_b32_e64 v90, v82, v80, s[42:43]
	v_cndmask_b32_e64 v83, v108, v247, s[38:39]
	v_cndmask_b32_e64 v82, v107, v247, s[38:39]
	v_pk_add_f32 v[82:83], v[88:89], v[82:83]
	ds_bpermute_b32 v88, v140, v82
	ds_bpermute_b32 v89, v140, v83
	ds_bpermute_b32 v92, v140, v84
	ds_bpermute_b32 v93, v140, v85
	ds_bpermute_b32 v94, v140, v86
	ds_bpermute_b32 v95, v140, v87
	s_waitcnt lgkmcnt(4)
	v_pk_add_f32 v[88:89], v[82:83], v[88:89]
	ds_bpermute_b32 v80, v142, v90
	s_waitcnt lgkmcnt(3)
	v_pk_add_f32 v[92:93], v[84:85], v[92:93]
	v_cndmask_b32_e64 v89, v89, v83, s[42:43]
	s_waitcnt lgkmcnt(1)
	v_pk_add_f32 v[94:95], v[86:87], v[94:95]
	v_cndmask_b32_e64 v88, v88, v82, s[42:43]
	v_cndmask_b32_e64 v93, v93, v85, s[42:43]
	v_cndmask_b32_e64 v92, v92, v84, s[42:43]
	v_cndmask_b32_e64 v95, v95, v87, s[42:43]
	v_cndmask_b32_e64 v94, v94, v86, s[42:43]
	ds_bpermute_b32 v81, v142, v91
	ds_bpermute_b32 v82, v142, v88
	ds_bpermute_b32 v83, v142, v89
	ds_bpermute_b32 v84, v142, v92
	ds_bpermute_b32 v85, v142, v93
	ds_bpermute_b32 v86, v142, v94
	ds_bpermute_b32 v87, v142, v95
	ds_bpermute_b32 v108, v143, v99
	ds_bpermute_b32 v107, v143, v100
	ds_bpermute_b32 v109, v143, v102
	ds_bpermute_b32 v115, v143, v103
	s_waitcnt lgkmcnt(10)
	v_pk_add_f32 v[80:81], v[90:91], v[80:81]
	s_waitcnt lgkmcnt(8)
	v_pk_add_f32 v[82:83], v[88:89], v[82:83]
	s_waitcnt lgkmcnt(6)
	v_pk_add_f32 v[84:85], v[92:93], v[84:85]
	s_waitcnt lgkmcnt(4)
	v_pk_add_f32 v[86:87], v[94:95], v[86:87]
	s_and_saveexec_b64 s[0:1], s[2:3]
	s_cbranch_execz .LBB0_375
	ds_write_b128 v149, v[80:83]
	ds_write_b128 v149, v[84:87] offset:16

; DI void unpack8(const u32x4 w, float (&f)[8]) { f[0] = bf_lo(w.x); f[1] = bf_hi(w.x); f[2] = bf_lo(w.y); f[3] = bf_hi(w.y); f[4] = bf_lo(w.z); f[5] = bf_hi(w.z); f[6] = bf_lo(w.w); f[7] = bf_hi(w.w); }
; DI void phase_prep(int l, int wv, bool last, bool dry = false) {
;     ...
;         const int chunk = item >> 4, h = (item >> 1) & 7, hc = (item & 1) * 64 + cg * 8, row = chunk * 64 + pp, c0 = h * DK + hc;
;         bf16* prow = F.PROJ + (size_t)row * INW;
;         bool hasp, hasn;
;         if (row < NLAT) { hasp = pp != 0; hasn = pp != 63; } else { const int t = (row - NLAT) & (CTXL - 1); hasp = t != 0; hasn = t != CTXL - 1; }
;         const bool full = !(last && row >= NLAT);
;         if (full) {   float cb[8], cc[8], cv[8], up[8], un[8], t0[8], t1[8], ya[8];
;     ...
;             if (hasp) { unpack8(P.ccp, t0); unpack8(P.cvp, t1);
; #pragma unroll
;                 for (int j = 0; j < 8; ++j) up[j] = t0[j] * t1[j]; }
;     ...
;     while (item < NITEM) {
;         const int n1 = item + F.G, n2 = item + 2 * F.G;
;         if (n1 < NITEM) item_load(n1, PB);
;         item_compute(item, PA);
;         if (n1 >= NITEM) break;
;         if (n2 < NITEM) item_load(n2, PA);
;         item_compute(n1, PB);
.LBB0_388:
	s_add_i32 s0, s59, s68
	s_cmpk_gt_i32 s0, 0x11ff
	s_cbranch_scc1 .LBB0_392
.LBB0_392:
	s_ashr_i32 s30, s65, 4
	s_add_i32 s0, s61, s64
	v_and_or_b32 v150, s0, 64, v137
	v_lshl_add_u32 v120, s30, 6, v136
	v_readlane_b32 s0, v254, 33
	s_bfe_u32 s31, s65, 0x30001
	v_cmp_gt_i32_e32 vcc, s89, v120
	v_readlane_b32 s1, v254, 34
	v_lshl_or_b32 v128, s31, 7, v150
	v_ashrrev_i32_e32 v121, 31, v120
	s_or_b64 s[24:25], s[0:1], vcc
	s_and_saveexec_b64 s[26:27], s[24:25]
	s_cbranch_execz .LBB0_398
	s_waitcnt lgkmcnt(0)
	v_and_b32_e32 v80, 0xff, v120
	v_cmp_gt_i32_e32 vcc, s89, v120
	v_mov_b32_e32 v116, 0
	v_mov_b32_e32 v118, 0
	v_cndmask_b32_e32 v81, v80, v136, vcc
	v_cmp_ne_u32_e64 s[0:1], 0, v81
	v_mov_b32_e32 v119, 0
	v_mov_b32_e32 v122, 0
	v_mov_b32_e32 v123, 0
	v_mov_b32_e32 v126, 0
	v_mov_b32_e32 v127, 0
	v_mov_b32_e32 v112, 0
	v_mov_b32_e32 v113, 0
	s_and_saveexec_b64 s[28:29], s[0:1]
	s_cbranch_execz .LBB0_395
	v_lshlrev_b32_e32 v83, 16, v40
	v_and_b32_e32 v82, 0xffff0000, v40
	v_lshlrev_b32_e32 v85, 16, v48
	v_and_b32_e32 v84, 0xffff0000, v48
	v_lshlrev_b32_e32 v87, 16, v41
	v_and_b32_e32 v86, 0xffff0000, v41
	v_lshlrev_b32_e32 v89, 16, v49
	v_and_b32_e32 v88, 0xffff0000, v49
	v_lshlrev_b32_e32 v90, 16, v42
	v_and_b32_e32 v91, 0xffff0000, v42
	v_lshlrev_b32_e32 v92, 16, v50
	v_and_b32_e32 v93, 0xffff0000, v50
	v_lshlrev_b32_e32 v94, 16, v43
	v_and_b32_e32 v95, 0xffff0000, v43
	v_lshlrev_b32_e32 v96, 16, v51
	v_and_b32_e32 v97, 0xffff0000, v51
	v_pk_mul_f32 v[118:119], v[84:85], v[82:83]
	v_pk_mul_f32 v[122:123], v[88:89], v[86:87]
	v_pk_mul_f32 v[126:127], v[92:93], v[90:91]
	v_pk_mul_f32 v[112:113], v[96:97], v[94:95]

; DI void unpack8(const u32x4 w, float (&f)[8]) { f[0] = bf_lo(w.x); f[1] = bf_hi(w.x); f[2] = bf_lo(w.y); f[3] = bf_hi(w.y); f[4] = bf_lo(w.z); f[5] = bf_hi(w.z); f[6] = bf_lo(w.w); f[7] = bf_hi(w.w); }
; DI float frcp(float x) { return __builtin_amdgcn_rcpf(x); }
; DI void phase_prep(int l, int wv, bool last, bool dry = false) {
;     ...
;     auto item_load = [&](int item, PrepIn& P) {
;         const int chunk = item >> 4, h = (item >> 1) & 7, hc = (item & 1) * 64 + cg * 8, row = chunk * 64 + pp, c0 = h * DK + hc;
;         const bf16* prow = F.PROJ + (size_t)row * INW;
;         bool hasp, hasn;
;         if (row < NLAT) { hasp = pp != 0; hasn = pp != 63; } else { const int t = (row - NLAT) & (CTXL - 1); hasp = t != 0; hasn = t != CTXL - 1; }
;         const bf16* pprev = hasp ? prow - INW : prow; const bf16* pnext = hasn ? prow + INW : prow;
;         if (!(last && row >= NLAT)) {
;     ...
;         P.ccp = *(const u32x4*)(pprev + C_CC + c0); P.cvp = *(const u32x4*)(pprev + C_CV + c0); P.ccn = *(const u32x4*)(pnext + C_CC + c0); P.cvn = *(const u32x4*)(pnext + C_CV + c0);
;         P.q = *(const u32x4*)(prow + C_Q + c0); }
;         P.zf = *(const u32x4*)(prow + C_ZF + c0); P.zb = *(const u32x4*)(prow + C_ZB + c0); };
;     ...
;         float lff[8], lfb[8], kf[8], kb[8], qs[8];
;         {   float zf[8], zb[8], q[8];
;             unpack8(P.zf, zf); unpack8(P.zb, zb);
;             if (full) unpack8(P.q, q); else {
; #pragma unroll
;                 for (int i = 0; i < 8; ++i) q[i] = 0.f; }
;             const f32x4 lfa = *(const f32x4*)(lbt + c0), lfc = *(const f32x4*)(lbt + c0 + 4), lba = *(const f32x4*)(lbt + DC + c0), lbc = *(const f32x4*)(lbt + DC + c0 + 4);
; #pragma unroll
;             for (int i = 0; i < 8; ++i) { const float lbf = i < 4 ? lfa[i & 3] : lfc[i & 3], lbb = i < 4 ? lba[i & 3] : lbc[i & 3];
;                 const float ef = __expf(fminf(fmaxf(-zf[i], -80.f), 80.f)), eb = __expf(fminf(fmaxf(-zb[i], -80.f), 80.f)), sf = frcp(1.0f + ef), sb = frcp(1.0f + eb);
;                 lff[i] = __logf(fmaxf(lbf + (1.0f - lbf) * sf, F_MIN)); kf[i] = (1.0f - lbf) * (ef * sf);
;                 lfb[i] = __logf(fmaxf(lbb + (1.0f - lbb) * sb, F_MIN)); kb[i] = (1.0f - lbb) * (eb * sb);
;                 qs[i] = q[i] * frcp(1.0f + __expf(-q[i])) * QSCALE; }
.LBB0_398:
	s_or_b64 exec, exec, s[26:27]
	v_mov_b32_e32 v121, 0
	v_mov_b32_e32 v122, 0
	v_mov_b32_e32 v123, 0
	v_mov_b32_e32 v124, 0
	v_mov_b32_e32 v125, 0
	v_mov_b32_e32 v126, 0
	v_mov_b32_e32 v127, 0
	v_mov_b32_e32 v130, 0
	s_and_saveexec_b64 s[0:1], s[24:25]
	v_lshlrev_b32_e32 v121, 16, v68
	v_and_b32_e32 v122, 0xffff0000, v68
	v_lshlrev_b32_e32 v123, 16, v69
	v_and_b32_e32 v124, 0xffff0000, v69
	v_lshlrev_b32_e32 v125, 16, v70
	v_and_b32_e32 v126, 0xffff0000, v70
	v_lshlrev_b32_e32 v127, 16, v71
	v_and_b32_e32 v130, 0xffff0000, v71
	s_or_b64 exec, exec, s[0:1]
	v_lshlrev_b32_e32 v88, 2, v128
	global_load_dwordx4 v[84:87], v88, s[12:13] offset:16
	global_load_dwordx4 v[92:95], v88, s[12:13]
	s_waitcnt lgkmcnt(0)
	global_load_dwordx4 v[80:83], v88, s[22:23] offset:16
	s_nop 0
	global_load_dwordx4 v[88:91], v88, s[22:23]
	v_lshlrev_b32_e32 v98, 16, v72
	v_max_f32_e64 v98, -v98, -v98
	s_mov_b32 s27, 0xc2a00000
	v_med3_f32 v98, v98, s27, v245
	v_mul_f32_e32 v98, 0x3fb8aa3b, v98
	v_lshlrev_b32_e32 v111, 16, v76
	v_exp_f32_e32 v110, v98
	v_max_f32_e64 v98, -v111, -v111
	v_med3_f32 v98, v98, s27, v245
	v_mul_f32_e32 v98, 0x3fb8aa3b, v98
	v_exp_f32_e32 v111, v98
	v_add_f32_e32 v98, 1.0, v110
	v_rcp_f32_e32 v131, v98
	s_mov_b32 s26, 0x800000
	v_add_f32_e32 v98, 1.0, v111
	v_rcp_f32_e32 v132, v98
	s_mov_b32 s28, 0x3f317217
	s_mov_b32 s29, 0x7f800000
	v_and_b32_e32 v107, 0xffff0000, v72
	v_and_b32_e32 v112, 0xffff0000, v76
	v_lshlrev_b32_e32 v108, 16, v73
	v_lshlrev_b32_e32 v109, 16, v77
	v_and_b32_e32 v105, 0xffff0000, v73
	v_and_b32_e32 v106, 0xffff0000, v77
	v_lshlrev_b32_e32 v103, 16, v74
	v_lshlrev_b32_e32 v104, 16, v78
	v_and_b32_e32 v101, 0xffff0000, v74
	v_and_b32_e32 v102, 0xffff0000, v78
	v_lshlrev_b32_e32 v99, 16, v75
	v_lshlrev_b32_e32 v100, 16, v79
	v_and_b32_e32 v96, 0xffff0000, v75
	v_and_b32_e32 v97, 0xffff0000, v79
	s_barrier
	s_waitcnt vmcnt(3)
	v_sub_f32_e32 v172, 1.0, v84
	s_waitcnt vmcnt(2)
	v_sub_f32_e32 v133, 1.0, v92
	v_fma_f32 v92, v131, v133, v92
	v_max_f32_e32 v92, 0xda24260, v92
	v_cmp_gt_f32_e32 vcc, s26, v92
	s_waitcnt vmcnt(0)
	v_sub_f32_e32 v134, 1.0, v88
	v_fma_f32 v88, v132, v134, v88
	v_cndmask_b32_e64 v98, 0, 32, vcc
	v_ldexp_f32 v92, v92, v98
	v_log_f32_e32 v92, v92
	v_max_f32_e32 v88, 0xda24260, v88
	v_sub_f32_e32 v154, 1.0, v93
	v_sub_f32_e32 v155, 1.0, v89
	v_mul_f32_e32 v98, 0x3f317217, v92
	v_fma_f32 v98, v92, s28, -v98
	v_fmac_f32_e32 v98, 0x3377d1cf, v92
	v_fmac_f32_e32 v98, 0x3f317217, v92
	v_cmp_lt_f32_e64 s[0:1], |v92|, s29
	v_sub_f32_e32 v160, 1.0, v94
	v_sub_f32_e32 v161, 1.0, v90
	v_cndmask_b32_e64 v92, v92, v98, s[0:1]
	v_cndmask_b32_e32 v98, 0, v246, vcc
	s_add_i32 s96, s59, s68
	s_cmpk_gt_i32 s96, 0x11ff
	s_cbranch_scc1 .Lprep_pf_skip_B
	v_mov_b32_e32 v209, 0
	s_add_i32 s97, s60, s63
	s_add_i32 s96, s58, s64
	s_andn2_b32 s97, s97, 63
	v_add_u32_e32 v47, s97, v136
	s_and_b32 s96, s96, 0x3c0
	v_mov_b64_e32 v[44:45], s[8:9]
	v_or_b32_e32 v46, s96, v137
	v_mad_i64_i32 v[44:45], s[96:97], v47, s66, v[44:45]
	v_readlane_b32 s96, v254, 33
	v_cmp_gt_i32_e32 vcc, s89, v47
	v_readlane_b32 s97, v254, 34
	s_or_b64 s[96:97], s[96:97], vcc
	s_and_saveexec_b64 s[94:95], s[96:97]
	s_xor_b64 s[94:95], exec, s[94:95]
	s_cbranch_execz .LBB0_391
	v_and_b32_e32 v0, 0xff, v47
	s_movk_i32 s96, 0xff
	v_cmp_gt_i32_e32 vcc, s89, v47
	v_cmp_ne_u32_e64 s[96:97], s96, v0
	v_cndmask_b32_e64 v2, 0, 1, s[36:37]
	v_cndmask_b32_e32 v1, v0, v136, vcc
	v_cndmask_b32_e64 v0, 0, 1, s[96:97]
	v_cndmask_b32_e32 v0, v0, v2, vcc
	v_and_b32_e32 v0, 1, v0
	v_cmp_eq_u32_e32 vcc, 1, v0
	s_nop 1
	v_cndmask_b32_e32 v208, 0, v241, vcc
	v_lshl_add_u64 v[16:17], v[44:45], 0, v[208:209]
	v_cmp_eq_u32_e32 vcc, 0, v1
	v_lshlrev_b32_e32 v208, 1, v46
	v_lshl_add_u64 v[10:11], v[44:45], 0, v[208:209]
	v_cndmask_b32_e64 v1, -1, 0, vcc
	v_cndmask_b32_e64 v0, v251, 0, vcc
	v_lshl_add_u64 v[8:9], v[44:45], 0, v[0:1]
	v_add_co_u32_e32 v28, vcc, s67, v10
	v_lshl_add_u64 v[8:9], v[8:9], 0, v[208:209]
	s_nop 0
	v_addc_co_u32_e32 v29, vcc, 0, v11, vcc
	v_add_co_u32_e32 v12, vcc, 0x1000, v8
	v_lshl_add_u64 v[16:17], v[16:17], 0, v[208:209]
	s_nop 0
	v_addc_co_u32_e32 v13, vcc, 0, v9, vcc
	v_add_co_u32_e32 v20, vcc, 0x1000, v16
	global_load_dwordx4 v[0:3], v[10:11], off
	global_load_dwordx4 v[4:7], v[10:11], off offset:2048
	v_addc_co_u32_e32 v21, vcc, 0, v17, vcc
	global_load_dwordx4 v[8:11], v[8:9], off offset:2048
	s_nop 0
	global_load_dwordx4 v[12:15], v[12:13], off
	s_nop 0
	global_load_dwordx4 v[16:19], v[16:17], off offset:2048
	s_nop 0
	global_load_dwordx4 v[24:27], v[20:21], off
	s_nop 0
	global_load_dwordx4 v[20:23], v[28:29], off
	s_nop 0
	global_load_dwordx4 v[28:31], v[28:29], off offset:2048
.LBB0_391:
	s_andn2_saveexec_b64 s[96:97], s[94:95]
	s_or_b64 exec, exec, s[96:97]
	v_lshlrev_b32_e32 v208, 1, v46
	v_lshl_add_u64 v[44:45], v[44:45], 0, v[208:209]
	v_add_co_u32_e32 v52, vcc, 0x2000, v44
	s_nop 1
	v_addc_co_u32_e32 v53, vcc, 0, v45, vcc
	global_load_dwordx4 v[44:47], v[52:53], off
	s_nop 0
	global_load_dwordx4 v[52:55], v[52:53], off offset:2048
; DI float frcp(float x) { return __builtin_amdgcn_rcpf(x); }
; DI void phase_prep(int l, int wv, bool last, bool dry = false) {
;     ...
;             const f32x4 lfa = *(const f32x4*)(lbt + c0), lfc = *(const f32x4*)(lbt + c0 + 4), lba = *(const f32x4*)(lbt + DC + c0), lbc = *(const f32x4*)(lbt + DC + c0 + 4);
; #pragma unroll
;             for (int i = 0; i < 8; ++i) { const float lbf = i < 4 ? lfa[i & 3] : lfc[i & 3], lbb = i < 4 ? lba[i & 3] : lbc[i & 3];
;                 const float ef = __expf(fminf(fmaxf(-zf[i], -80.f), 80.f)), eb = __expf(fminf(fmaxf(-zb[i], -80.f), 80.f)), sf = frcp(1.0f + ef), sb = frcp(1.0f + eb);
;                 lff[i] = __logf(fmaxf(lbf + (1.0f - lbf) * sf, F_MIN)); kf[i] = (1.0f - lbf) * (ef * sf);
;                 lfb[i] = __logf(fmaxf(lbb + (1.0f - lbb) * sb, F_MIN)); kb[i] = (1.0f - lbb) * (eb * sb);
;                 qs[i] = q[i] * frcp(1.0f + __expf(-q[i])) * QSCALE; }
;         }
; #pragma unroll
;         for (int d = 1; d < 8; d <<= 1) {
; #pragma unroll
;             for (int i = 0; i < 8; ++i) { const float o = __shfl_up(lff[i], 8 * d); if (pl >= d) lff[i] += o; const float o2 = __shfl_down(lfb[i], 8 * d); if (pl + d < 8) lfb[i] += o2; } }
.Lprep_pf_skip_B:
	v_cmp_gt_f32_e32 vcc, s26, v88
	v_sub_f32_e32 v92, v92, v98
	v_sub_f32_e32 v166, 1.0, v95
	v_cndmask_b32_e64 v98, 0, 32, vcc
	v_ldexp_f32 v88, v88, v98
	v_log_f32_e32 v88, v88
	v_sub_f32_e32 v167, 1.0, v91
	v_sub_f32_e32 v173, 1.0, v80
	v_sub_f32_e32 v178, 1.0, v85
	v_mul_f32_e32 v98, 0x3f317217, v88
	v_fma_f32 v98, v88, s28, -v98
	v_fmac_f32_e32 v98, 0x3377d1cf, v88
	v_fmac_f32_e32 v98, 0x3f317217, v88
	v_cmp_lt_f32_e64 s[0:1], |v88|, s29
	v_sub_f32_e32 v179, 1.0, v81
	v_sub_f32_e32 v184, 1.0, v86
	v_cndmask_b32_e64 v88, v88, v98, s[0:1]
	v_cndmask_b32_e32 v98, 0, v246, vcc
	v_sub_f32_e32 v98, v88, v98
	v_max_f32_e64 v88, -v107, -v107
	v_med3_f32 v88, v88, s27, v245
	v_mul_f32_e32 v88, 0x3fb8aa3b, v88
	v_exp_f32_e32 v135, v88
	v_max_f32_e64 v88, -v112, -v112
	v_med3_f32 v88, v88, s27, v245
	v_mul_f32_e32 v88, 0x3fb8aa3b, v88
	v_exp_f32_e32 v151, v88
	v_add_f32_e32 v88, 1.0, v135
	v_rcp_f32_e32 v152, v88
	v_sub_f32_e32 v185, 1.0, v82
	v_add_f32_e32 v88, 1.0, v151
	v_rcp_f32_e32 v153, v88
	v_fma_f32 v88, v152, v154, v93
	v_max_f32_e32 v88, 0xda24260, v88
	v_cmp_gt_f32_e32 vcc, s26, v88
	v_sub_f32_e32 v190, 1.0, v87
	v_sub_f32_e32 v191, 1.0, v83
	v_cndmask_b32_e64 v93, 0, 32, vcc
	v_ldexp_f32 v88, v88, v93
	v_log_f32_e32 v88, v88
	s_nop 0
	v_mul_f32_e32 v93, 0x3f317217, v88
	v_fma_f32 v93, v88, s28, -v93
	v_fmac_f32_e32 v93, 0x3377d1cf, v88
	v_fmac_f32_e32 v93, 0x3f317217, v88
	v_cmp_lt_f32_e64 s[0:1], |v88|, s29
	s_nop 1
	v_cndmask_b32_e64 v88, v88, v93, s[0:1]
	v_cndmask_b32_e32 v93, 0, v246, vcc
	v_sub_f32_e32 v93, v88, v93
	v_fma_f32 v88, v153, v155, v89
	v_max_f32_e32 v88, 0xda24260, v88
	v_cmp_gt_f32_e32 vcc, s26, v88
	s_nop 1
	v_cndmask_b32_e64 v89, 0, 32, vcc
	v_ldexp_f32 v88, v88, v89
	v_log_f32_e32 v88, v88
	s_nop 0
	v_mul_f32_e32 v89, 0x3f317217, v88
	v_fma_f32 v89, v88, s28, -v89
	v_fmac_f32_e32 v89, 0x3377d1cf, v88
	v_fmac_f32_e32 v89, 0x3f317217, v88
	v_cmp_lt_f32_e64 s[0:1], |v88|, s29
	s_nop 1
	v_cndmask_b32_e64 v88, v88, v89, s[0:1]
	v_cndmask_b32_e32 v89, 0, v246, vcc
	v_sub_f32_e32 v107, v88, v89
	v_max_f32_e64 v88, -v108, -v108
	v_med3_f32 v88, v88, s27, v245
	v_mul_f32_e32 v88, 0x3fb8aa3b, v88
	v_exp_f32_e32 v156, v88
	v_max_f32_e64 v88, -v109, -v109
	v_med3_f32 v88, v88, s27, v245
	v_mul_f32_e32 v88, 0x3fb8aa3b, v88
	v_exp_f32_e32 v157, v88
	v_add_f32_e32 v88, 1.0, v156
	v_rcp_f32_e32 v158, v88
	v_add_f32_e32 v88, 1.0, v157
	v_rcp_f32_e32 v159, v88
	v_fma_f32 v88, v158, v160, v94
	v_max_f32_e32 v88, 0xda24260, v88
	v_cmp_gt_f32_e32 vcc, s26, v88
	s_nop 1
	v_cndmask_b32_e64 v89, 0, 32, vcc
	v_ldexp_f32 v88, v88, v89
	v_log_f32_e32 v88, v88
	s_nop 0
	v_mul_f32_e32 v89, 0x3f317217, v88
	v_fma_f32 v89, v88, s28, -v89
	v_fmac_f32_e32 v89, 0x3377d1cf, v88
	v_fmac_f32_e32 v89, 0x3f317217, v88
	v_cmp_lt_f32_e64 s[0:1], |v88|, s29
	s_nop 1
	v_cndmask_b32_e64 v88, v88, v89, s[0:1]
	v_cndmask_b32_e32 v89, 0, v246, vcc
	v_sub_f32_e32 v88, v88, v89
	v_fma_f32 v89, v159, v161, v90
	v_max_f32_e32 v89, 0xda24260, v89
	v_cmp_gt_f32_e32 vcc, s26, v89
	s_nop 1
	v_cndmask_b32_e64 v90, 0, 32, vcc
	v_ldexp_f32 v89, v89, v90
	v_log_f32_e32 v89, v89
	s_nop 0
	v_mul_f32_e32 v90, 0x3f317217, v89
	v_fma_f32 v90, v89, s28, -v90
	v_fmac_f32_e32 v90, 0x3377d1cf, v89
	v_fmac_f32_e32 v90, 0x3f317217, v89
	v_cmp_lt_f32_e64 s[0:1], |v89|, s29
	s_nop 1
	v_cndmask_b32_e64 v89, v89, v90, s[0:1]
	v_cndmask_b32_e32 v90, 0, v246, vcc
	v_sub_f32_e32 v90, v89, v90
	v_max_f32_e64 v89, -v105, -v105
	v_med3_f32 v89, v89, s27, v245
	v_mul_f32_e32 v89, 0x3fb8aa3b, v89
	v_exp_f32_e32 v162, v89
	v_max_f32_e64 v89, -v106, -v106
	v_med3_f32 v89, v89, s27, v245
	v_mul_f32_e32 v89, 0x3fb8aa3b, v89
	v_exp_f32_e32 v163, v89
	v_add_f32_e32 v89, 1.0, v162
	v_rcp_f32_e32 v164, v89
	ds_bpermute_b32 v105, v138, v93
	v_add_f32_e32 v89, 1.0, v163
	v_rcp_f32_e32 v165, v89
	v_fmac_f32_e32 v95, v164, v166
	v_max_f32_e32 v89, 0xda24260, v95
	v_cmp_gt_f32_e32 vcc, s26, v89
	v_fmac_f32_e32 v91, v165, v167
	v_max_f32_e32 v91, 0xda24260, v91
	v_cndmask_b32_e64 v94, 0, 32, vcc
	v_ldexp_f32 v89, v89, v94
	v_log_f32_e32 v89, v89
	ds_bpermute_b32 v95, v139, v98
	v_mul_f32_e32 v94, 0x3f317217, v89
	v_fma_f32 v94, v89, s28, -v94
	v_fmac_f32_e32 v94, 0x3377d1cf, v89
	v_fmac_f32_e32 v94, 0x3f317217, v89
	v_cmp_lt_f32_e64 s[0:1], |v89|, s29
	s_waitcnt lgkmcnt(0)
; DI float frcp(float x) { return __builtin_amdgcn_rcpf(x); }
; DI void phase_prep(int l, int wv, bool last, bool dry = false) {
;     ...
;             const f32x4 lfa = *(const f32x4*)(lbt + c0), lfc = *(const f32x4*)(lbt + c0 + 4), lba = *(const f32x4*)(lbt + DC + c0), lbc = *(const f32x4*)(lbt + DC + c0 + 4);
; #pragma unroll
;             for (int i = 0; i < 8; ++i) { const float lbf = i < 4 ? lfa[i & 3] : lfc[i & 3], lbb = i < 4 ? lba[i & 3] : lbc[i & 3];
;                 const float ef = __expf(fminf(fmaxf(-zf[i], -80.f), 80.f)), eb = __expf(fminf(fmaxf(-zb[i], -80.f), 80.f)), sf = frcp(1.0f + ef), sb = frcp(1.0f + eb);
;                 lff[i] = __logf(fmaxf(lbf + (1.0f - lbf) * sf, F_MIN)); kf[i] = (1.0f - lbf) * (ef * sf);
;                 lfb[i] = __logf(fmaxf(lbb + (1.0f - lbb) * sb, F_MIN)); kb[i] = (1.0f - lbb) * (eb * sb);
;                 qs[i] = q[i] * frcp(1.0f + __expf(-q[i])) * QSCALE; }
;         }
; #pragma unroll
;         for (int d = 1; d < 8; d <<= 1) {
; #pragma unroll
;             for (int i = 0; i < 8; ++i) { const float o = __shfl_up(lff[i], 8 * d); if (pl >= d) lff[i] += o; const float o2 = __shfl_down(lfb[i], 8 * d); if (pl + d < 8) lfb[i] += o2; } }
	v_cndmask_b32_e64 v95, v247, v95, s[40:41]
	v_add_f32_e32 v95, v95, v98
	v_cndmask_b32_e64 v89, v89, v94, s[0:1]
	v_cndmask_b32_e32 v94, 0, v246, vcc
	v_cmp_gt_f32_e32 vcc, s26, v91
	v_sub_f32_e32 v89, v89, v94
	ds_bpermute_b32 v108, v138, v89
	v_cndmask_b32_e64 v94, 0, 32, vcc
	v_ldexp_f32 v91, v91, v94
	v_log_f32_e32 v91, v91
	s_nop 0
	v_mul_f32_e32 v94, 0x3f317217, v91
	v_fma_f32 v94, v91, s28, -v94
	v_fmac_f32_e32 v94, 0x3377d1cf, v91
	v_fmac_f32_e32 v94, 0x3f317217, v91
	v_cmp_lt_f32_e64 s[0:1], |v91|, s29
	s_nop 1
	v_cndmask_b32_e64 v91, v91, v94, s[0:1]
	v_cndmask_b32_e32 v94, 0, v246, vcc
	v_sub_f32_e32 v91, v91, v94
	v_max_f32_e64 v94, -v103, -v103
	v_med3_f32 v94, v94, s27, v245
	v_mul_f32_e32 v94, 0x3fb8aa3b, v94
	v_exp_f32_e32 v168, v94
	v_max_f32_e64 v94, -v104, -v104
	v_med3_f32 v94, v94, s27, v245
	v_mul_f32_e32 v94, 0x3fb8aa3b, v94
	v_exp_f32_e32 v169, v94
	v_add_f32_e32 v94, 1.0, v168
	v_rcp_f32_e32 v170, v94
	v_add_f32_e32 v94, 1.0, v169
	v_rcp_f32_e32 v171, v94
	v_fma_f32 v84, v170, v172, v84
	v_max_f32_e32 v84, 0xda24260, v84
	v_cmp_gt_f32_e32 vcc, s26, v84
	v_fma_f32 v80, v171, v173, v80
	v_max_f32_e32 v80, 0xda24260, v80
	v_cndmask_b32_e64 v94, 0, 32, vcc
	v_ldexp_f32 v84, v84, v94
	v_log_f32_e32 v84, v84
	s_nop 0
	v_mul_f32_e32 v94, 0x3f317217, v84
	v_fma_f32 v94, v84, s28, -v94
	v_fmac_f32_e32 v94, 0x3377d1cf, v84
	v_fmac_f32_e32 v94, 0x3f317217, v84
	v_cmp_lt_f32_e64 s[0:1], |v84|, s29
	s_nop 1
	v_cndmask_b32_e64 v84, v84, v94, s[0:1]
	v_cndmask_b32_e32 v94, 0, v246, vcc
	v_cmp_gt_f32_e32 vcc, s26, v80
	v_sub_f32_e32 v84, v84, v94
	ds_bpermute_b32 v109, v138, v84
	v_cndmask_b32_e64 v94, 0, 32, vcc
	v_ldexp_f32 v80, v80, v94
	v_log_f32_e32 v80, v80
	s_nop 0
	v_mul_f32_e32 v94, 0x3f317217, v80
	v_fma_f32 v94, v80, s28, -v94
	v_fmac_f32_e32 v94, 0x3377d1cf, v80
	v_fmac_f32_e32 v94, 0x3f317217, v80
	v_cmp_lt_f32_e64 s[0:1], |v80|, s29
	s_nop 1
	v_cndmask_b32_e64 v80, v80, v94, s[0:1]
	v_cndmask_b32_e32 v94, 0, v246, vcc
	v_sub_f32_e32 v80, v80, v94
	v_max_f32_e64 v94, -v101, -v101
	v_med3_f32 v94, v94, s27, v245
	v_mul_f32_e32 v94, 0x3fb8aa3b, v94
	v_exp_f32_e32 v174, v94
	v_max_f32_e64 v94, -v102, -v102
	v_med3_f32 v94, v94, s27, v245
	v_mul_f32_e32 v94, 0x3fb8aa3b, v94
	v_exp_f32_e32 v175, v94
	v_add_f32_e32 v94, 1.0, v174
	v_rcp_f32_e32 v176, v94
	v_add_f32_e32 v94, 1.0, v175
	v_rcp_f32_e32 v177, v94
	v_fma_f32 v85, v176, v178, v85
	v_max_f32_e32 v85, 0xda24260, v85
	v_cmp_gt_f32_e32 vcc, s26, v85
	v_fma_f32 v81, v177, v179, v81
	v_max_f32_e32 v81, 0xda24260, v81
	v_cndmask_b32_e64 v94, 0, 32, vcc
	v_ldexp_f32 v85, v85, v94
	v_log_f32_e32 v85, v85
	s_nop 0
	v_mul_f32_e32 v94, 0x3f317217, v85
	v_fma_f32 v94, v85, s28, -v94
	v_fmac_f32_e32 v94, 0x3377d1cf, v85
	v_fmac_f32_e32 v94, 0x3f317217, v85
	v_cmp_lt_f32_e64 s[0:1], |v85|, s29
	s_nop 1
	v_cndmask_b32_e64 v85, v85, v94, s[0:1]
	v_cndmask_b32_e32 v94, 0, v246, vcc
	v_cmp_gt_f32_e32 vcc, s26, v81
	v_sub_f32_e32 v85, v85, v94
	ds_bpermute_b32 v112, v138, v85
	v_cndmask_b32_e64 v94, 0, 32, vcc
	v_ldexp_f32 v81, v81, v94
	v_log_f32_e32 v81, v81
	s_nop 0
	v_mul_f32_e32 v94, 0x3f317217, v81
	v_fma_f32 v94, v81, s28, -v94
	v_fmac_f32_e32 v94, 0x3377d1cf, v81
	v_fmac_f32_e32 v94, 0x3f317217, v81
	v_cmp_lt_f32_e64 s[0:1], |v81|, s29
	s_nop 1
	v_cndmask_b32_e64 v81, v81, v94, s[0:1]
	v_cndmask_b32_e32 v94, 0, v246, vcc
	v_sub_f32_e32 v81, v81, v94
	v_max_f32_e64 v94, -v99, -v99
	v_med3_f32 v94, v94, s27, v245
	v_mul_f32_e32 v94, 0x3fb8aa3b, v94
	v_exp_f32_e32 v180, v94
	v_max_f32_e64 v94, -v100, -v100
	v_med3_f32 v94, v94, s27, v245
	v_mul_f32_e32 v94, 0x3fb8aa3b, v94
	v_exp_f32_e32 v181, v94
	v_add_f32_e32 v94, 1.0, v180
	v_rcp_f32_e32 v182, v94
	v_add_f32_e32 v94, 1.0, v181
	v_rcp_f32_e32 v183, v94
	v_fma_f32 v86, v182, v184, v86
	v_max_f32_e32 v86, 0xda24260, v86
	v_cmp_gt_f32_e32 vcc, s26, v86
	v_fma_f32 v82, v183, v185, v82
	v_max_f32_e32 v82, 0xda24260, v82
	v_cndmask_b32_e64 v94, 0, 32, vcc
	v_ldexp_f32 v86, v86, v94
	v_log_f32_e32 v86, v86
	s_nop 0
	v_mul_f32_e32 v94, 0x3f317217, v86
	v_fma_f32 v94, v86, s28, -v94
	v_fmac_f32_e32 v94, 0x3377d1cf, v86
	v_fmac_f32_e32 v94, 0x3f317217, v86
	v_cmp_lt_f32_e64 s[0:1], |v86|, s29
	s_nop 1
	v_cndmask_b32_e64 v86, v86, v94, s[0:1]
	v_cndmask_b32_e32 v94, 0, v246, vcc
	v_cmp_gt_f32_e32 vcc, s26, v82
	v_sub_f32_e32 v86, v86, v94
	ds_bpermute_b32 v114, v138, v86
	v_cndmask_b32_e64 v94, 0, 32, vcc
	v_ldexp_f32 v82, v82, v94
	v_log_f32_e32 v82, v82
	s_nop 0
	v_mul_f32_e32 v94, 0x3f317217, v82
	v_fma_f32 v94, v82, s28, -v94
	v_fmac_f32_e32 v94, 0x3377d1cf, v82
	v_fmac_f32_e32 v94, 0x3f317217, v82
	v_cmp_lt_f32_e64 s[0:1], |v82|, s29
	s_nop 1
	v_cndmask_b32_e64 v82, v82, v94, s[0:1]
	v_cndmask_b32_e32 v94, 0, v246, vcc
	v_sub_f32_e32 v82, v82, v94
	v_max_f32_e64 v94, -v96, -v96
	v_med3_f32 v94, v94, s27, v245
	v_mul_f32_e32 v94, 0x3fb8aa3b, v94
	ds_bpermute_b32 v96, v139, v107
	v_exp_f32_e32 v186, v94
	v_max_f32_e64 v94, -v97, -v97
	v_med3_f32 v94, v94, s27, v245
	v_mul_f32_e32 v94, 0x3fb8aa3b, v94
	v_exp_f32_e32 v187, v94
	v_add_f32_e32 v94, 1.0, v186
	s_waitcnt lgkmcnt(0)
; #define LAS __attribute__((address_space(3)))
; DI void phase_prep(int l, int wv, bool last, bool dry = false) {
;     ...
;         for (int d = 1; d < 8; d <<= 1) {
; #pragma unroll
;             for (int i = 0; i < 8; ++i) { const float o = __shfl_up(lff[i], 8 * d); if (pl >= d) lff[i] += o; const float o2 = __shfl_down(lfb[i], 8 * d); if (pl + d < 8) lfb[i] += o2; } }
;         __syncthreads();
;         if (pl == 7) { *(LAS f32x4*)(L + O_TOTF + (w * 64 + cg * 8) * 4) = (f32x4){lff[0], lff[1], lff[2], lff[3]}; *(LAS f32x4*)(L + O_TOTF + (w * 64 + cg * 8 + 4) * 4) = (f32x4){lff[4], lff[5], lff[6], lff[7]}; }
;         if (pl == 0) { *(LAS f32x4*)(L + O_TOTB + (w * 64 + cg * 8) * 4) = (f32x4){lfb[0], lfb[1], lfb[2], lfb[3]}; *(LAS f32x4*)(L + O_TOTB + (w * 64 + cg * 8 + 4) * 4) = (f32x4){lfb[4], lfb[5], lfb[6], lfb[7]}; }
	v_cndmask_b32_e64 v96, v247, v96, s[40:41]
	v_rcp_f32_e32 v188, v94
	v_add_f32_e32 v97, v107, v96
	ds_bpermute_b32 v96, v139, v90
	v_add_f32_e32 v94, 1.0, v187
	v_fmac_f32_e32 v87, v188, v190
	v_max_f32_e32 v87, 0xda24260, v87
	v_cmp_gt_f32_e32 vcc, s26, v87
	s_waitcnt lgkmcnt(0)
	v_cndmask_b32_e64 v96, v247, v96, s[40:41]
	v_add_f32_e32 v90, v90, v96
	ds_bpermute_b32 v96, v139, v91
	v_rcp_f32_e32 v189, v94
	v_cndmask_b32_e64 v94, 0, 32, vcc
	v_ldexp_f32 v87, v87, v94
	v_log_f32_e32 v87, v87
	s_waitcnt lgkmcnt(0)
	v_cndmask_b32_e64 v96, v247, v96, s[40:41]
	v_add_f32_e32 v91, v91, v96
	ds_bpermute_b32 v96, v139, v80
	v_mul_f32_e32 v94, 0x3f317217, v87
	v_fma_f32 v94, v87, s28, -v94
	v_fmac_f32_e32 v94, 0x3377d1cf, v87
	v_fmac_f32_e32 v83, v189, v191
	v_fmac_f32_e32 v94, 0x3f317217, v87
	v_cmp_lt_f32_e64 s[0:1], |v87|, s29
	v_max_f32_e32 v83, 0xda24260, v83
	s_waitcnt lgkmcnt(0)
	v_cndmask_b32_e64 v96, v247, v96, s[40:41]
	v_cndmask_b32_e64 v87, v87, v94, s[0:1]
	v_cndmask_b32_e32 v94, 0, v246, vcc
	v_cmp_gt_f32_e32 vcc, s26, v83
	v_sub_f32_e32 v87, v87, v94
	v_add_f32_e32 v80, v80, v96
	v_cndmask_b32_e64 v94, 0, 32, vcc
	ds_bpermute_b32 v96, v139, v81
	v_ldexp_f32 v83, v83, v94
	v_log_f32_e32 v83, v83
	ds_bpermute_b32 v107, v138, v88
	ds_bpermute_b32 v115, v138, v87
	s_waitcnt lgkmcnt(2)
	v_cndmask_b32_e64 v96, v247, v96, s[40:41]
	v_mul_f32_e32 v94, 0x3f317217, v83
	v_add_f32_e32 v81, v81, v96
	ds_bpermute_b32 v96, v139, v82
	v_fma_f32 v94, v83, s28, -v94
	v_fmac_f32_e32 v94, 0x3377d1cf, v83
	v_fmac_f32_e32 v94, 0x3f317217, v83
	v_cmp_lt_f32_e64 s[0:1], |v83|, s29
	s_waitcnt lgkmcnt(0)
	v_cndmask_b32_e64 v96, v247, v96, s[40:41]
	v_add_f32_e32 v82, v82, v96
	v_cndmask_b32_e64 v83, v83, v94, s[0:1]
	v_cndmask_b32_e32 v94, 0, v246, vcc
	v_sub_f32_e32 v83, v83, v94
	ds_bpermute_b32 v96, v139, v83
	ds_bpermute_b32 v94, v138, v92
	s_waitcnt lgkmcnt(1)
	v_cndmask_b32_e64 v96, v247, v96, s[40:41]
	v_add_f32_e32 v83, v83, v96
	ds_bpermute_b32 v96, v141, v95
	s_waitcnt lgkmcnt(0)
	v_add_f32_e32 v96, v95, v96
	v_cndmask_b32_e64 v96, v95, v96, s[44:45]
	ds_bpermute_b32 v95, v141, v97
	ds_bpermute_b32 v104, v143, v96
	s_waitcnt lgkmcnt(1)
	v_add_f32_e32 v95, v97, v95
	v_cndmask_b32_e64 v97, v97, v95, s[44:45]
	ds_bpermute_b32 v95, v141, v90
	ds_bpermute_b32 v106, v143, v97
	s_waitcnt lgkmcnt(1)
	v_add_f32_e32 v95, v90, v95
	v_cndmask_b32_e64 v98, v90, v95, s[44:45]
	ds_bpermute_b32 v90, v141, v91
	v_cndmask_b32_e64 v95, v115, v247, s[38:39]
	s_waitcnt lgkmcnt(0)
	v_add_f32_e32 v90, v91, v90
	v_cndmask_b32_e64 v99, v91, v90, s[44:45]
	ds_bpermute_b32 v90, v141, v80
	s_waitcnt lgkmcnt(0)
	v_add_f32_e32 v90, v80, v90
	v_cndmask_b32_e64 v100, v80, v90, s[44:45]
	ds_bpermute_b32 v80, v141, v81
	s_waitcnt lgkmcnt(0)
	v_add_f32_e32 v80, v81, v80
	v_cndmask_b32_e64 v101, v81, v80, s[44:45]
	ds_bpermute_b32 v80, v141, v82
	v_cndmask_b32_e64 v81, v105, v247, s[38:39]
	ds_bpermute_b32 v105, v143, v98
	ds_bpermute_b32 v113, v143, v101
	s_waitcnt lgkmcnt(2)
	v_add_f32_e32 v80, v82, v80
	v_cndmask_b32_e64 v102, v82, v80, s[44:45]
	ds_bpermute_b32 v80, v141, v83
	s_waitcnt lgkmcnt(0)
	v_add_f32_e32 v80, v83, v80
	v_cndmask_b32_e64 v103, v83, v80, s[44:45]
	v_cndmask_b32_e64 v80, v94, v247, s[38:39]
	v_pk_add_f32 v[80:81], v[92:93], v[80:81]
	ds_bpermute_b32 v82, v140, v80
	ds_bpermute_b32 v83, v140, v81
	v_cndmask_b32_e64 v93, v112, v247, s[38:39]
	v_cndmask_b32_e64 v92, v109, v247, s[38:39]
	v_cndmask_b32_e64 v94, v114, v247, s[38:39]
	v_pk_add_f32 v[84:85], v[84:85], v[92:93]
	s_waitcnt lgkmcnt(0)
	v_pk_add_f32 v[82:83], v[80:81], v[82:83]
	v_pk_add_f32 v[86:87], v[86:87], v[94:95]
	v_cndmask_b32_e64 v91, v83, v81, s[42:43]
	v_cndmask_b32_e64 v90, v82, v80, s[42:43]
	v_cndmask_b32_e64 v83, v108, v247, s[38:39]
	v_cndmask_b32_e64 v82, v107, v247, s[38:39]
	v_pk_add_f32 v[82:83], v[88:89], v[82:83]
	ds_bpermute_b32 v88, v140, v82
	ds_bpermute_b32 v89, v140, v83
	ds_bpermute_b32 v92, v140, v84
	ds_bpermute_b32 v93, v140, v85
	ds_bpermute_b32 v94, v140, v86
	ds_bpermute_b32 v95, v140, v87
	s_waitcnt lgkmcnt(4)
	v_pk_add_f32 v[88:89], v[82:83], v[88:89]
	ds_bpermute_b32 v80, v142, v90
	s_waitcnt lgkmcnt(3)
	v_pk_add_f32 v[92:93], v[84:85], v[92:93]
	v_cndmask_b32_e64 v89, v89, v83, s[42:43]
	s_waitcnt lgkmcnt(1)
	v_pk_add_f32 v[94:95], v[86:87], v[94:95]
	v_cndmask_b32_e64 v88, v88, v82, s[42:43]
	v_cndmask_b32_e64 v93, v93, v85, s[42:43]
	v_cndmask_b32_e64 v92, v92, v84, s[42:43]
	v_cndmask_b32_e64 v95, v95, v87, s[42:43]
	v_cndmask_b32_e64 v94, v94, v86, s[42:43]
	ds_bpermute_b32 v81, v142, v91
	ds_bpermute_b32 v82, v142, v88
	ds_bpermute_b32 v83, v142, v89
	ds_bpermute_b32 v84, v142, v92
	ds_bpermute_b32 v85, v142, v93
	ds_bpermute_b32 v86, v142, v94
	ds_bpermute_b32 v87, v142, v95
	ds_bpermute_b32 v108, v143, v99
	ds_bpermute_b32 v107, v143, v100
	ds_bpermute_b32 v109, v143, v102
	ds_bpermute_b32 v115, v143, v103
	s_waitcnt lgkmcnt(10)
	v_pk_add_f32 v[80:81], v[90:91], v[80:81]
	s_waitcnt lgkmcnt(8)
	v_pk_add_f32 v[82:83], v[88:89], v[82:83]
	s_waitcnt lgkmcnt(6)
	v_pk_add_f32 v[84:85], v[92:93], v[84:85]
	s_waitcnt lgkmcnt(4)
	v_pk_add_f32 v[86:87], v[94:95], v[86:87]
	s_and_saveexec_b64 s[0:1], s[2:3]
	s_cbranch_execz .LBB0_402
	ds_write_b128 v149, v[80:83]
	ds_write_b128 v149, v[84:87] offset:16
